# retention intra-chunk loop: K fragment reads batched with counted waits, V transpose reads hoisted above the decay-mask VALU
# speedup vs baseline: 1.0141x; 1.0108x over previous
; #define LAS __attribute__((address_space(3)))
; DI int crow(int r, int hi) { return (r & 3) + 8 * (r >> 2) + 4 * hi; }
; DI s16x4 vtr(const LAS unsigned char* p) { typedef short v4i16_t __attribute__((ext_vector_type(4))); return __builtin_bit_cast(s16x4, __builtin_amdgcn_ds_read_tr16_b64_v4i16((LAS v4i16_t*)p)); }
; DI bf16x8 cat8(s16x4 lo, s16x4 hi) { return (bf16x8){lo[0], lo[1], lo[2], lo[3], hi[0], hi[1], hi[2], hi[3]}; }
; #define MFMA32(a, b, c) __builtin_amdgcn_mfma_f32_32x32x16_bf16((a), (b), (c), 0, 0, 0)
; DI void phase_ret_out(const Params& p, const Grp& G, int layer, LAS unsigned char* lds, int tid, int wave, int lane, bool dry) {
;     ...
;         for (int rb = 0; rb < 4; ++rb) {
;             f32x16 sacc = {};
; #pragma unroll
;             for (int d0 = 0; d0 < 4; ++d0) { const bf16x8 A = *(const LAS bf16x8*)(Kt + (32 * rb + l31) * RP + (hh * 64 + 16 * d0 + 8 * hi) * 2); sacc = MFMA32(A, qf[d0], sacc); }
; #pragma unroll
;             for (int r = 0; r < 16; ++r) { const int mloc = 32 * rb + crow(r, hi); const int df = nl - mloc; const float D = df >= 0 ? __builtin_amdgcn_exp2f(lgf * (float)df) : __builtin_amdgcn_exp2f(lgb * (float)(-df)); sacc[r] *= D; }
; #pragma unroll
;             for (int s2 = 0; s2 < 2; ++s2) { const bf16x8 A = pack8(sacc, s2); const int rowa = (32 * rb + 16 * s2 + 4 * hi + q4) * RP;
; #pragma unroll
;                 for (int cb = 0; cb < 2; ++cb) { const int colb = (hh * 64 + 32 * cb + 16 * blk + 4 * p4) * 2;
;                     const bf16x8 B = cat8(vtr(Vt + rowa + colb), vtr(Vt + rowa + 8 * RP + colb)); o[cb] = MFMA32(A, B, o[cb]); } }
;         }
.LBB0_422:
	v_add_u32_e32 v142, 0, v137
	ds_read_b128 v[32:35], v142
	ds_read_b128 v[138:141], v142 offset:32
	ds_read_b128 v[236:239], v142 offset:64
	ds_read_b128 v[248:251], v142 offset:96
	v_add_u32_e32 v137, 0x2200, v137
	s_waitcnt lgkmcnt(3)
	v_mfma_f32_32x32x16_bf16 v[32:47], v[32:35], v[112:115], 0
	s_waitcnt lgkmcnt(2)
	v_mfma_f32_32x32x16_bf16 v[32:47], v[138:141], v[116:119], v[32:47]
	s_waitcnt lgkmcnt(1)
	v_mfma_f32_32x32x16_bf16 v[32:47], v[236:239], v[120:123], v[32:47]
	v_add_u32_e32 v142, s0, v187
	v_cmp_gt_i32_e32 vcc, 0, v142
	s_sub_i32 s0, s0, 32
	s_cmpk_lg_i32 s0, 0xff80
	s_waitcnt lgkmcnt(0)
	v_mfma_f32_32x32x16_bf16 v[32:47], v[248:251], v[124:127], v[32:47]
	v_sub_u32_e32 v138, 0, v142
	v_max_i32_e32 v138, v142, v138
	v_cvt_f32_u32_e32 v138, v138
	v_cndmask_b32_e32 v139, v134, v135, vcc
	v_sub_u32_e32 v140, 1, v142
	v_mul_f32_e32 v138, v139, v138
	v_add_u32_e32 v139, -1, v142
	v_max_i32_e32 v140, v139, v140
	v_cvt_f32_u32_e32 v140, v140
	v_cmp_gt_i32_e32 vcc, 0, v139
	v_exp_f32_e32 v138, v138
	s_nop 0
	v_cndmask_b32_e32 v139, v134, v135, vcc
	v_mul_f32_e32 v139, v139, v140
	v_exp_f32_e32 v139, v139
	v_sub_u32_e32 v140, 3, v142
	v_pk_mul_f32 v[32:33], v[138:139], v[32:33]
	v_add_u32_e32 v138, -2, v142
	v_sub_u32_e32 v139, 2, v142
	v_max_i32_e32 v139, v138, v139
	v_cvt_f32_u32_e32 v139, v139
	v_cmp_gt_i32_e32 vcc, 0, v138
	v_cvt_pk_bf16_f32 v32, v32, v33
	s_nop 0
	v_cndmask_b32_e32 v138, v134, v135, vcc
	v_mul_f32_e32 v138, v138, v139
	v_add_u32_e32 v139, -3, v142
	v_max_i32_e32 v140, v139, v140
	v_cvt_f32_u32_e32 v140, v140
	v_cmp_gt_i32_e32 vcc, 0, v139
	v_exp_f32_e32 v138, v138
	s_nop 0
	v_cndmask_b32_e32 v139, v134, v135, vcc
	v_mul_f32_e32 v139, v139, v140
	v_exp_f32_e32 v139, v139
	v_sub_u32_e32 v140, 9, v142
	v_pk_mul_f32 v[34:35], v[138:139], v[34:35]
	v_add_u32_e32 v138, -8, v142
	v_sub_u32_e32 v139, 8, v142
	v_max_i32_e32 v139, v138, v139
	v_cvt_f32_u32_e32 v139, v139
	v_cmp_gt_i32_e32 vcc, 0, v138
	v_cvt_pk_bf16_f32 v33, v34, v35
	s_nop 0
	v_cndmask_b32_e32 v138, v134, v135, vcc
	v_mul_f32_e32 v138, v138, v139
	v_add_u32_e32 v139, -9, v142
	v_max_i32_e32 v140, v139, v140
	v_cvt_f32_u32_e32 v140, v140
	v_cmp_gt_i32_e32 vcc, 0, v139
	v_exp_f32_e32 v138, v138
	s_nop 0
	v_cndmask_b32_e32 v139, v134, v135, vcc
	v_mul_f32_e32 v139, v139, v140
	v_exp_f32_e32 v139, v139
	v_sub_u32_e32 v140, 11, v142
	v_pk_mul_f32 v[138:139], v[138:139], v[36:37]
	v_add_u32_e32 v36, -10, v142
	v_sub_u32_e32 v37, 10, v142
	v_max_i32_e32 v37, v36, v37
	v_cvt_f32_u32_e32 v37, v37
	v_cmp_gt_i32_e32 vcc, 0, v36
	v_cvt_pk_bf16_f32 v34, v138, v139
	v_add_u32_e32 v138, 0, v136
	ds_read_b64_tr_b16 v[236:237], v138 offset:34816
	ds_read_b64_tr_b16 v[238:239], v138 offset:36992
	ds_read_b64_tr_b16 v[248:249], v138 offset:34880
	ds_read_b64_tr_b16 v[250:251], v138 offset:37056
	ds_read_b64_tr_b16 v[232:233], v138 offset:39168
	ds_read_b64_tr_b16 v[234:235], v138 offset:41344
	v_cndmask_b32_e32 v36, v134, v135, vcc
	v_mul_f32_e32 v36, v36, v37
	v_add_u32_e32 v37, -11, v142
	v_max_i32_e32 v140, v37, v140
	v_cvt_f32_u32_e32 v140, v140
	v_cmp_gt_i32_e32 vcc, 0, v37
	v_exp_f32_e32 v36, v36
	v_add_u32_e32 v136, 0x2200, v136
	v_cndmask_b32_e32 v37, v134, v135, vcc
	v_mul_f32_e32 v37, v37, v140
	v_exp_f32_e32 v37, v37
	s_nop 0
	v_pk_mul_f32 v[140:141], v[36:37], v[38:39]
	v_add_u32_e32 v36, -16, v142
	v_sub_u32_e32 v37, 16, v142
	v_max_i32_e32 v37, v36, v37
	v_cvt_f32_u32_e32 v37, v37
	v_cmp_gt_i32_e32 vcc, 0, v36
	v_sub_u32_e32 v38, 17, v142
	v_sub_u32_e32 v39, 18, v142
	v_cndmask_b32_e32 v36, v134, v135, vcc
	v_mul_f32_e32 v36, v36, v37
	v_subrev_u32_e32 v37, 17, v142
	v_max_i32_e32 v38, v37, v38
	v_cvt_f32_u32_e32 v38, v38
	v_cmp_gt_i32_e32 vcc, 0, v37
	v_exp_f32_e32 v36, v36
	v_cvt_pk_bf16_f32 v35, v140, v141
	v_cndmask_b32_e32 v37, v134, v135, vcc
	v_mul_f32_e32 v37, v37, v38
	v_subrev_u32_e32 v38, 18, v142
	v_max_i32_e32 v39, v38, v39
	v_exp_f32_e32 v37, v37
	v_cvt_f32_u32_e32 v39, v39
	v_cmp_gt_i32_e32 vcc, 0, v38
	v_pk_mul_f32 v[36:37], v[36:37], v[40:41]
	s_nop 0
	v_cndmask_b32_e32 v38, v134, v135, vcc
	v_mul_f32_e32 v38, v38, v39
	v_subrev_u32_e32 v39, 19, v142
	v_sub_u32_e32 v40, 19, v142
	v_max_i32_e32 v40, v39, v40
	v_cvt_f32_u32_e32 v40, v40
	v_cmp_gt_i32_e32 vcc, 0, v39
	v_sub_u32_e32 v41, 24, v142
	v_exp_f32_e32 v38, v38
	v_cndmask_b32_e32 v39, v134, v135, vcc
	v_mul_f32_e32 v39, v39, v40
	v_subrev_u32_e32 v40, 24, v142
	v_max_i32_e32 v41, v40, v41
	v_exp_f32_e32 v39, v39
	v_cvt_f32_u32_e32 v41, v41
	v_cmp_gt_i32_e32 vcc, 0, v40
	v_pk_mul_f32 v[38:39], v[38:39], v[42:43]
	s_nop 0
	v_cndmask_b32_e32 v40, v134, v135, vcc
	v_mul_f32_e32 v40, v40, v41
	v_subrev_u32_e32 v41, 25, v142
	v_sub_u32_e32 v42, 25, v142
	v_max_i32_e32 v42, v41, v42
	v_cvt_f32_u32_e32 v42, v42
	v_cmp_gt_i32_e32 vcc, 0, v41
	v_sub_u32_e32 v43, 26, v142
	v_exp_f32_e32 v40, v40
	v_cndmask_b32_e32 v41, v134, v135, vcc
	v_mul_f32_e32 v41, v41, v42
	v_subrev_u32_e32 v42, 26, v142
	v_max_i32_e32 v43, v42, v43
	v_exp_f32_e32 v41, v41
	v_cvt_f32_u32_e32 v43, v43
	v_cmp_gt_i32_e32 vcc, 0, v42
	v_pk_mul_f32 v[40:41], v[40:41], v[44:45]
	s_nop 0
	v_cndmask_b32_e32 v42, v134, v135, vcc
	v_mul_f32_e32 v42, v42, v43
	v_subrev_u32_e32 v43, 27, v142
	v_sub_u32_e32 v44, 27, v142
	v_max_i32_e32 v44, v43, v44
	v_cvt_f32_u32_e32 v44, v44
	v_cmp_gt_i32_e32 vcc, 0, v43
	v_exp_f32_e32 v42, v42
	s_nop 0
	v_cndmask_b32_e32 v43, v134, v135, vcc
	v_mul_f32_e32 v43, v43, v44
	v_exp_f32_e32 v43, v43
	s_nop 0
	v_pk_mul_f32 v[42:43], v[42:43], v[46:47]
	s_waitcnt lgkmcnt(4)
	v_mfma_f32_32x32x16_bf16 v[0:15], v[32:35], v[236:239], v[0:15]
	s_waitcnt lgkmcnt(2)
	v_mfma_f32_32x32x16_bf16 v[16:31], v[32:35], v[248:251], v[16:31]
	v_cvt_pk_bf16_f32 v32, v36, v37
	v_cvt_pk_bf16_f32 v33, v38, v39
	v_cvt_pk_bf16_f32 v34, v40, v41
	v_cvt_pk_bf16_f32 v35, v42, v43
	ds_read_b64_tr_b16 v[36:37], v138 offset:39232
	ds_read_b64_tr_b16 v[38:39], v138 offset:41408
	s_waitcnt lgkmcnt(2)
	v_mfma_f32_32x32x16_bf16 v[0:15], v[32:35], v[232:235], v[0:15]
	s_waitcnt lgkmcnt(0)
	v_mfma_f32_32x32x16_bf16 v[16:31], v[32:35], v[36:39], v[16:31]
	s_cbranch_scc1 .LBB0_422
; #define LAS __attribute__((address_space(3)))
; DI int crow(int r, int hi) { return (r & 3) + 8 * (r >> 2) + 4 * hi; }
; #define MFMA32(a, b, c) __builtin_amdgcn_mfma_f32_32x32x16_bf16((a), (b), (c), 0, 0, 0)
; DI void phase_ret_out(const Params& p, const Grp& G, int layer, LAS unsigned char* lds, int tid, int wave, int lane, bool dry) {
;     ...
; #pragma unroll 1
;         for (int dir = 0; dir < 2; ++dir) {
;             const LAS bf16_t* S = Sl + (hh * 2 + dir) * 4096; f32x16 t[2]; t[0] = f32x16{}; t[1] = f32x16{};
; #pragma unroll
;             for (int ks = 0; ks < 4; ++ks) {
; #pragma unroll
;                 for (int cb = 0; cb < 2; ++cb) { const LAS bf16_t* sp = S + (16 * ks + 8 * hi) * 64 + 32 * cb + l31;
;                     u32x4 w; w.x = (unsigned)sp[0] | ((unsigned)sp[64] << 16); w.y = (unsigned)sp[128] | ((unsigned)sp[192] << 16); w.z = (unsigned)sp[256] | ((unsigned)sp[320] << 16); w.w = (unsigned)sp[384] | ((unsigned)sp[448] << 16);
;                     t[cb] = MFMA32(qf[ks], __builtin_bit_cast(bf16x8, w), t[cb]); }
;                 asm volatile("" ::: "memory"); }
; #pragma unroll
;             for (int r = 0; r < 16; ++r) { const int nrow = 32 * qg + crow(r, hi); const float sc = dir == 0 ? __builtin_amdgcn_exp2f(lgf * (float)(nrow + 1)) : __builtin_amdgcn_exp2f(lgb * (float)(128 - nrow));
;                 o[0][r] += t[0][r] * sc; o[1][r] += t[1][r] * sc; }
	v_mul_f32_e32 v32, v135, v153
	v_exp_f32_e32 v188, v32
	v_mul_f32_e32 v32, v134, v154
	v_exp_f32_e32 v189, v32
	v_mul_f32_e32 v32, v135, v155
	v_exp_f32_e32 v190, v32
	v_mul_f32_e32 v32, v134, v156
	v_exp_f32_e32 v191, v32
	v_mul_f32_e32 v32, v135, v157
	v_exp_f32_e32 v192, v32
	v_mul_f32_e32 v32, v134, v158
	v_exp_f32_e32 v196, v32
	v_mul_f32_e32 v32, v135, v159
	v_exp_f32_e32 v197, v32
	v_mul_f32_e32 v32, v134, v160
	v_exp_f32_e32 v198, v32
	v_mul_f32_e32 v32, v135, v161
	v_exp_f32_e32 v199, v32
	v_mul_f32_e32 v32, v134, v162
	v_exp_f32_e32 v200, v32
	v_mul_f32_e32 v32, v135, v163
	v_exp_f32_e32 v201, v32
	v_mul_f32_e32 v32, v134, v164
	v_exp_f32_e32 v202, v32
	v_mul_f32_e32 v32, v135, v165
	v_exp_f32_e32 v203, v32
	v_mul_f32_e32 v32, v134, v166
	v_exp_f32_e32 v204, v32
	v_mul_f32_e32 v32, v135, v167
	v_exp_f32_e32 v205, v32
	v_mul_f32_e32 v32, v134, v168
	v_exp_f32_e32 v206, v32
	v_mul_f32_e32 v32, v135, v169
	v_exp_f32_e32 v207, v32
	v_mul_f32_e32 v32, v134, v170
	v_exp_f32_e32 v208, v32
	v_mul_f32_e32 v32, v135, v171
	v_exp_f32_e32 v209, v32
	v_mul_f32_e32 v32, v134, v172
	v_exp_f32_e32 v210, v32
	v_mul_f32_e32 v32, v135, v173
	v_exp_f32_e32 v211, v32
	v_mul_f32_e32 v32, v134, v174
	v_exp_f32_e32 v216, v32
	v_mul_f32_e32 v32, v135, v175
	v_exp_f32_e32 v217, v32
	v_mul_f32_e32 v32, v134, v176
	v_exp_f32_e32 v218, v32
	v_mul_f32_e32 v32, v135, v177
	v_exp_f32_e32 v219, v32
	v_mul_f32_e32 v32, v134, v178
	v_exp_f32_e32 v220, v32
	v_mul_f32_e32 v32, v135, v179
	v_exp_f32_e32 v221, v32
	v_mul_f32_e32 v32, v134, v180
	v_exp_f32_e32 v222, v32
	v_mul_f32_e32 v32, v135, v181
	v_exp_f32_e32 v223, v32
	v_mul_f32_e32 v32, v134, v182
	v_exp_f32_e32 v224, v32
	v_mul_f32_e32 v32, v135, v183
	v_exp_f32_e32 v225, v32
	v_mul_f32_e32 v32, v134, v184
	v_exp_f32_e32 v226, v32
	s_mov_b32 s0, 0
	s_mov_b64 s[30:31], -1
	v_mov_b32_e32 v148, v1
	v_mov_b32_e32 v146, v3
	v_mov_b32_e32 v144, v5
	v_mov_b32_e32 v142, v7
	v_mov_b32_e32 v140, v9
	v_mov_b32_e32 v138, v11
	v_mov_b32_e32 v136, v13
	v_mov_b32_e32 v134, v15
	v_mov_b32_e32 v1, v16
	v_mov_b32_e32 v149, v17
	v_mov_b32_e32 v3, v18
	v_mov_b32_e32 v147, v19
	v_mov_b32_e32 v5, v20
	v_mov_b32_e32 v145, v21
	v_mov_b32_e32 v7, v22
	v_mov_b32_e32 v143, v23
	v_mov_b32_e32 v9, v24
	v_mov_b32_e32 v141, v25
	v_mov_b32_e32 v11, v26
	v_mov_b32_e32 v139, v27
	v_mov_b32_e32 v13, v28
	v_mov_b32_e32 v137, v29
	v_mov_b32_e32 v15, v30
	v_mov_b32_e32 v135, v31
